# add static s_setprio 1 for waves 4-7 inside the hand-scheduled K-loops
# baseline (speedup 1.0000x reference)
; __device__ __forceinline__ void gemm_stream256(f32x4 (&acc)[8][4], const Seg& cur, const Seg& nxt, bool has_next, bool first, int& st, unsigned char* lds, int tid) {
;     ...
;     for (int kt = 0; kt < nk; ++kt) {
;         const int idx = kt + 1;
;         const bool incur = idx < nk, doi = incur || has_next;
;         if (!late && doi) { if (incur) issue(apc, bpc, cur.lda, cur.ldb, idx * 64, s0 ^ 1); else issue(apn, bpn, nxt.lda, nxt.ldb, 0, s0 ^ 1); }
;         const unsigned char* As = lds + s0 * STAGE;
;         const unsigned char* Bs = As + 256 * 128;
; #pragma unroll
;         for (int ks = 0; ks < 2; ++ks) {
;             if (ks == 1 && late && doi) { if (incur) issue(apc, bpc, cur.lda, cur.ldb, idx * 64, s0 ^ 1); else issue(apn, bpn, nxt.lda, nxt.ldb, 0, s0 ^ 1); }
;             bf16x8 af[8], bfr[4];
;             const int co = ((ks * 4 + fq) ^ sz) * 16;
; #pragma unroll
;             for (int m = 0; m < 8; ++m) af[m] = *(const bf16x8*)(As + (wr * 128 + m * 16 + fr) * 128 + co);
; #pragma unroll
;             for (int n = 0; n < 4; ++n) bfr[n] = *(const bf16x8*)(Bs + (wc * 64 + n * 16 + fr) * 128 + co);
; #pragma unroll
;             for (int m = 0; m < 8; ++m)
; #pragma unroll
;                 for (int n = 0; n < 4; ++n) acc[m][n] = __builtin_amdgcn_mfma_f32_16x16x32_bf16(bfr[n], af[m], acc[m][n], 0, 0, 0);
;         }
;         asm volatile("s_waitcnt vmcnt(0) lgkmcnt(0)" ::: "memory");
;         __builtin_amdgcn_s_barrier();
;         asm volatile("" ::: "memory");
;         s0 ^= 1;
;     }
.LBB0_313:
	s_mov_b64 s[76:77], 0x42080
	s_mov_b64 s[70:71], 0x62080
	s_and_b32 s50, s42, 7
	s_lshl_b32 s50, s50, 8
	s_mov_b32 s51, 0
	s_mov_b32 s75, 0
	s_and_b64 vcc, exec, s[46:47]
	s_cbranch_vccz .Lp1_kloop_np
	s_setprio 1
.Lp1_kloop_np:
	s_lshl_b32 s54, s44, 16
	s_xor_b32 s57, s54, 0x10000
	s_add_i32 s56, s18, s57
	v_add3_u32 v160, s54, v159, v165
	v_add3_u32 v133, s54, v159, v164
	v_add3_u32 v251, s54, v162, v165
	v_add3_u32 v250, s54, v162, v164
	ds_read_b128 v[166:169], v160 offset:32768
	ds_read_b128 v[170:173], v160 offset:34816
	ds_read_b128 v[174:177], v160 offset:36864
	ds_read_b128 v[178:181], v160 offset:38912
	ds_read_b128 v[230:233], v133
	ds_read_b128 v[234:237], v133 offset:2048
	ds_read_b128 v[238:241], v133 offset:4096
	ds_read_b128 v[242:245], v133 offset:6144
	v_lshl_add_u64 v[128:129], v[138:139], 0, s[50:51]
	v_lshl_add_u64 v[130:131], v[140:141], 0, s[50:51]
	v_lshl_add_u64 v[150:151], v[128:129], 0, s[94:95]
	s_mov_b32 m0, s56
	s_nop 0
	global_load_lds_dwordx4 v[150:151], off
	v_lshl_add_u64 v[152:153], v[128:129], 0, s[14:15]
	s_add_i32 m0, s56, 0x2000
	s_nop 0
	global_load_lds_dwordx4 v[152:153], off
	v_lshl_add_u64 v[150:151], v[128:129], 0, s[96:97]
	s_add_i32 m0, s56, 0x4000
	s_nop 0
	global_load_lds_dwordx4 v[150:151], off
	v_lshl_add_u64 v[152:153], v[128:129], 0, s[12:13]
	s_add_i32 m0, s56, 0x6000
	s_nop 0
	global_load_lds_dwordx4 v[152:153], off
	ds_read_b128 v[214:217], v251 offset:32768
	ds_read_b128 v[218:221], v251 offset:34816
	ds_read_b128 v[222:225], v251 offset:36864
	ds_read_b128 v[226:229], v251 offset:38912
	s_waitcnt lgkmcnt(11)
	ds_read_b128 v[246:249], v133 offset:8192
	s_waitcnt lgkmcnt(11)
	ds_read_b128 v[182:185], v133 offset:10240
	s_waitcnt lgkmcnt(11)
	ds_read_b128 v[142:145], v133 offset:12288
	s_waitcnt lgkmcnt(11)
	ds_read_b128 v[146:149], v133 offset:14336
	s_waitcnt lgkmcnt(11)
	v_mfma_f32_16x16x32_bf16 v[124:127], v[166:169], v[230:233], v[124:127]
	v_mfma_f32_16x16x32_bf16 v[120:123], v[170:173], v[230:233], v[120:123]
	v_mfma_f32_16x16x32_bf16 v[116:119], v[174:177], v[230:233], v[116:119]
	v_mfma_f32_16x16x32_bf16 v[112:115], v[178:181], v[230:233], v[112:115]
	v_lshl_add_u64 v[150:151], v[130:131], 0, s[16:17]
	s_add_i32 m0, s56, 0x8000
	s_nop 0
	global_load_lds_dwordx4 v[150:151], off
	ds_read_b128 v[230:233], v250
	s_waitcnt lgkmcnt(11)
	v_mfma_f32_16x16x32_bf16 v[108:111], v[166:169], v[234:237], v[108:111]
	v_mfma_f32_16x16x32_bf16 v[104:107], v[170:173], v[234:237], v[104:107]
	v_mfma_f32_16x16x32_bf16 v[100:103], v[174:177], v[234:237], v[100:103]
	v_mfma_f32_16x16x32_bf16 v[96:99], v[178:181], v[234:237], v[96:99]
	v_lshl_add_u64 v[152:153], v[130:131], 0, s[24:25]
	s_add_i32 m0, s56, 0xa000
	s_nop 0
	global_load_lds_dwordx4 v[152:153], off
	ds_read_b128 v[234:237], v250 offset:2048
	s_waitcnt lgkmcnt(11)
	v_mfma_f32_16x16x32_bf16 v[92:95], v[166:169], v[238:241], v[92:95]
	v_mfma_f32_16x16x32_bf16 v[88:91], v[170:173], v[238:241], v[88:91]
	v_mfma_f32_16x16x32_bf16 v[84:87], v[174:177], v[238:241], v[84:87]
	v_mfma_f32_16x16x32_bf16 v[80:83], v[178:181], v[238:241], v[80:83]
	v_lshl_add_u64 v[150:151], v[130:131], 0, s[76:77]
	s_add_i32 m0, s56, 0xc000
	s_nop 0
	global_load_lds_dwordx4 v[150:151], off
	ds_read_b128 v[238:241], v250 offset:4096
	s_waitcnt lgkmcnt(11)
	v_mfma_f32_16x16x32_bf16 v[76:79], v[166:169], v[242:245], v[76:79]
	v_mfma_f32_16x16x32_bf16 v[72:75], v[170:173], v[242:245], v[72:75]
	v_mfma_f32_16x16x32_bf16 v[64:67], v[174:177], v[242:245], v[64:67]
	v_mfma_f32_16x16x32_bf16 v[60:63], v[178:181], v[242:245], v[60:63]
	v_lshl_add_u64 v[152:153], v[130:131], 0, s[70:71]
	s_add_i32 m0, s56, 0xe000
	s_nop 0
	global_load_lds_dwordx4 v[152:153], off
	ds_read_b128 v[242:245], v250 offset:6144
	s_waitcnt lgkmcnt(7)
	v_mfma_f32_16x16x32_bf16 v[56:59], v[166:169], v[246:249], v[56:59]
	v_mfma_f32_16x16x32_bf16 v[52:55], v[170:173], v[246:249], v[52:55]
	v_mfma_f32_16x16x32_bf16 v[48:51], v[174:177], v[246:249], v[48:51]
	v_mfma_f32_16x16x32_bf16 v[44:47], v[178:181], v[246:249], v[44:47]
	ds_read_b128 v[246:249], v250 offset:8192
	s_waitcnt lgkmcnt(7)
	v_mfma_f32_16x16x32_bf16 v[40:43], v[166:169], v[182:185], v[40:43]
	v_mfma_f32_16x16x32_bf16 v[36:39], v[170:173], v[182:185], v[36:39]
	v_mfma_f32_16x16x32_bf16 v[32:35], v[174:177], v[182:185], v[32:35]
	v_mfma_f32_16x16x32_bf16 v[28:31], v[178:181], v[182:185], v[28:31]
	ds_read_b128 v[182:185], v250 offset:10240
	s_waitcnt lgkmcnt(7)
	v_mfma_f32_16x16x32_bf16 v[24:27], v[166:169], v[142:145], v[24:27]
	v_mfma_f32_16x16x32_bf16 v[20:23], v[170:173], v[142:145], v[20:23]
	v_mfma_f32_16x16x32_bf16 v[16:19], v[174:177], v[142:145], v[16:19]
	v_mfma_f32_16x16x32_bf16 v[12:15], v[178:181], v[142:145], v[12:15]
	ds_read_b128 v[142:145], v250 offset:12288
	s_waitcnt lgkmcnt(7)
	v_mfma_f32_16x16x32_bf16 v[8:11], v[166:169], v[146:149], v[8:11]
	v_mfma_f32_16x16x32_bf16 v[4:7], v[170:173], v[146:149], v[4:7]
	v_mfma_f32_16x16x32_bf16 v[0:3], v[174:177], v[146:149], v[0:3]
	v_mfma_f32_16x16x32_bf16 v[68:71], v[178:181], v[146:149], v[68:71]
	ds_read_b128 v[146:149], v250 offset:14336
	s_waitcnt lgkmcnt(7)
	v_mfma_f32_16x16x32_bf16 v[124:127], v[214:217], v[230:233], v[124:127]
	v_mfma_f32_16x16x32_bf16 v[120:123], v[218:221], v[230:233], v[120:123]
	v_mfma_f32_16x16x32_bf16 v[116:119], v[222:225], v[230:233], v[116:119]
	v_mfma_f32_16x16x32_bf16 v[112:115], v[226:229], v[230:233], v[112:115]
	s_waitcnt lgkmcnt(6)
	v_mfma_f32_16x16x32_bf16 v[108:111], v[214:217], v[234:237], v[108:111]
	v_mfma_f32_16x16x32_bf16 v[104:107], v[218:221], v[234:237], v[104:107]
	v_mfma_f32_16x16x32_bf16 v[100:103], v[222:225], v[234:237], v[100:103]
	v_mfma_f32_16x16x32_bf16 v[96:99], v[226:229], v[234:237], v[96:99]
	s_waitcnt lgkmcnt(5)
	v_mfma_f32_16x16x32_bf16 v[92:95], v[214:217], v[238:241], v[92:95]
	v_mfma_f32_16x16x32_bf16 v[88:91], v[218:221], v[238:241], v[88:91]
	v_mfma_f32_16x16x32_bf16 v[84:87], v[222:225], v[238:241], v[84:87]
	v_mfma_f32_16x16x32_bf16 v[80:83], v[226:229], v[238:241], v[80:83]
	s_waitcnt lgkmcnt(4)
	v_mfma_f32_16x16x32_bf16 v[76:79], v[214:217], v[242:245], v[76:79]
	v_mfma_f32_16x16x32_bf16 v[72:75], v[218:221], v[242:245], v[72:75]
	v_mfma_f32_16x16x32_bf16 v[64:67], v[222:225], v[242:245], v[64:67]
	v_mfma_f32_16x16x32_bf16 v[60:63], v[226:229], v[242:245], v[60:63]
	s_add_u32 s50, s50, 0x80
	s_cmpk_eq_i32 s50, 0x780
	s_cselect_b32 s50, 0, s50
	s_add_i32 s75, s75, 1
	s_xor_b32 s44, s44, 1
	s_waitcnt vmcnt(0) lgkmcnt(0)
	s_barrier
; __device__ __forceinline__ void gemm_stream256(f32x4 (&acc)[8][4], const Seg& cur, const Seg& nxt, bool has_next, bool first, int& st, unsigned char* lds, int tid) {
;     ...
;     for (int kt = 0; kt < nk; ++kt) {
;         const int idx = kt + 1;
;         const bool incur = idx < nk, doi = incur || has_next;
;         if (!late && doi) { if (incur) issue(apc, bpc, cur.lda, cur.ldb, idx * 64, s0 ^ 1); else issue(apn, bpn, nxt.lda, nxt.ldb, 0, s0 ^ 1); }
;         const unsigned char* As = lds + s0 * STAGE;
;         const unsigned char* Bs = As + 256 * 128;
; #pragma unroll
;         for (int ks = 0; ks < 2; ++ks) {
;             if (ks == 1 && late && doi) { if (incur) issue(apc, bpc, cur.lda, cur.ldb, idx * 64, s0 ^ 1); else issue(apn, bpn, nxt.lda, nxt.ldb, 0, s0 ^ 1); }
;             bf16x8 af[8], bfr[4];
;             const int co = ((ks * 4 + fq) ^ sz) * 16;
; #pragma unroll
;             for (int m = 0; m < 8; ++m) af[m] = *(const bf16x8*)(As + (wr * 128 + m * 16 + fr) * 128 + co);
; #pragma unroll
;             for (int n = 0; n < 4; ++n) bfr[n] = *(const bf16x8*)(Bs + (wc * 64 + n * 16 + fr) * 128 + co);
; #pragma unroll
;             for (int m = 0; m < 8; ++m)
; #pragma unroll
;                 for (int n = 0; n < 4; ++n) acc[m][n] = __builtin_amdgcn_mfma_f32_16x16x32_bf16(bfr[n], af[m], acc[m][n], 0, 0, 0);
;         }
;         asm volatile("s_waitcnt vmcnt(0) lgkmcnt(0)" ::: "memory");
;         __builtin_amdgcn_s_barrier();
;         asm volatile("" ::: "memory");
;         s0 ^= 1;
;     }
.Lp1_kloop:
	s_lshl_b32 s54, s44, 16
	s_xor_b32 s57, s54, 0x10000
	s_add_i32 s56, s18, s57
	v_add3_u32 v160, s54, v159, v165
	v_add3_u32 v133, s54, v159, v164
	v_add3_u32 v251, s54, v162, v165
	v_add3_u32 v250, s54, v162, v164
	ds_read_b128 v[166:169], v160 offset:32768
	ds_read_b128 v[170:173], v160 offset:34816
	ds_read_b128 v[174:177], v160 offset:36864
	ds_read_b128 v[178:181], v160 offset:38912
	ds_read_b128 v[230:233], v133
	ds_read_b128 v[234:237], v133 offset:2048
	ds_read_b128 v[238:241], v133 offset:4096
	ds_read_b128 v[242:245], v133 offset:6144
	v_lshl_add_u64 v[128:129], v[138:139], 0, s[50:51]
	v_lshl_add_u64 v[130:131], v[140:141], 0, s[50:51]
	v_mfma_f32_16x16x32_bf16 v[56:59], v[214:217], v[246:249], v[56:59]
	v_mfma_f32_16x16x32_bf16 v[52:55], v[218:221], v[246:249], v[52:55]
	v_mfma_f32_16x16x32_bf16 v[48:51], v[222:225], v[246:249], v[48:51]
	v_mfma_f32_16x16x32_bf16 v[44:47], v[226:229], v[246:249], v[44:47]
	v_lshl_add_u64 v[150:151], v[128:129], 0, s[94:95]
	s_mov_b32 m0, s56
	s_nop 0
	global_load_lds_dwordx4 v[150:151], off
	v_mfma_f32_16x16x32_bf16 v[40:43], v[214:217], v[182:185], v[40:43]
	v_mfma_f32_16x16x32_bf16 v[36:39], v[218:221], v[182:185], v[36:39]
	v_mfma_f32_16x16x32_bf16 v[32:35], v[222:225], v[182:185], v[32:35]
	v_mfma_f32_16x16x32_bf16 v[28:31], v[226:229], v[182:185], v[28:31]
	v_lshl_add_u64 v[152:153], v[128:129], 0, s[14:15]
	s_add_i32 m0, s56, 0x2000
	s_nop 0
	global_load_lds_dwordx4 v[152:153], off
	v_mfma_f32_16x16x32_bf16 v[24:27], v[214:217], v[142:145], v[24:27]
	v_mfma_f32_16x16x32_bf16 v[20:23], v[218:221], v[142:145], v[20:23]
	v_mfma_f32_16x16x32_bf16 v[16:19], v[222:225], v[142:145], v[16:19]
	v_mfma_f32_16x16x32_bf16 v[12:15], v[226:229], v[142:145], v[12:15]
	v_lshl_add_u64 v[150:151], v[128:129], 0, s[96:97]
	s_add_i32 m0, s56, 0x4000
	s_nop 0
	global_load_lds_dwordx4 v[150:151], off
	v_mfma_f32_16x16x32_bf16 v[8:11], v[214:217], v[146:149], v[8:11]
	v_mfma_f32_16x16x32_bf16 v[4:7], v[218:221], v[146:149], v[4:7]
	v_mfma_f32_16x16x32_bf16 v[0:3], v[222:225], v[146:149], v[0:3]
	v_mfma_f32_16x16x32_bf16 v[68:71], v[226:229], v[146:149], v[68:71]
	v_lshl_add_u64 v[152:153], v[128:129], 0, s[12:13]
	s_add_i32 m0, s56, 0x6000
	s_nop 0
	global_load_lds_dwordx4 v[152:153], off
	s_waitcnt lgkmcnt(0)
	ds_read_b128 v[214:217], v251 offset:32768
	ds_read_b128 v[218:221], v251 offset:34816
	ds_read_b128 v[222:225], v251 offset:36864
	ds_read_b128 v[226:229], v251 offset:38912
	ds_read_b128 v[246:249], v133 offset:8192
	ds_read_b128 v[182:185], v133 offset:10240
	ds_read_b128 v[142:145], v133 offset:12288
	ds_read_b128 v[146:149], v133 offset:14336
	v_mfma_f32_16x16x32_bf16 v[124:127], v[166:169], v[230:233], v[124:127]
	v_mfma_f32_16x16x32_bf16 v[120:123], v[170:173], v[230:233], v[120:123]
	v_mfma_f32_16x16x32_bf16 v[116:119], v[174:177], v[230:233], v[116:119]
	v_mfma_f32_16x16x32_bf16 v[112:115], v[178:181], v[230:233], v[112:115]
	v_lshl_add_u64 v[150:151], v[130:131], 0, s[16:17]
	s_add_i32 m0, s56, 0x8000
	s_nop 0
	global_load_lds_dwordx4 v[150:151], off
	ds_read_b128 v[230:233], v250
	v_mfma_f32_16x16x32_bf16 v[108:111], v[166:169], v[234:237], v[108:111]
	v_mfma_f32_16x16x32_bf16 v[104:107], v[170:173], v[234:237], v[104:107]
	v_mfma_f32_16x16x32_bf16 v[100:103], v[174:177], v[234:237], v[100:103]
	v_mfma_f32_16x16x32_bf16 v[96:99], v[178:181], v[234:237], v[96:99]
	v_lshl_add_u64 v[152:153], v[130:131], 0, s[24:25]
	s_add_i32 m0, s56, 0xa000
	s_nop 0
	global_load_lds_dwordx4 v[152:153], off
	ds_read_b128 v[234:237], v250 offset:2048
	v_mfma_f32_16x16x32_bf16 v[92:95], v[166:169], v[238:241], v[92:95]
	v_mfma_f32_16x16x32_bf16 v[88:91], v[170:173], v[238:241], v[88:91]
	v_mfma_f32_16x16x32_bf16 v[84:87], v[174:177], v[238:241], v[84:87]
	v_mfma_f32_16x16x32_bf16 v[80:83], v[178:181], v[238:241], v[80:83]
	v_lshl_add_u64 v[150:151], v[130:131], 0, s[76:77]
	s_add_i32 m0, s56, 0xc000
	s_nop 0
	global_load_lds_dwordx4 v[150:151], off
	ds_read_b128 v[238:241], v250 offset:4096
	v_mfma_f32_16x16x32_bf16 v[76:79], v[166:169], v[242:245], v[76:79]
	v_mfma_f32_16x16x32_bf16 v[72:75], v[170:173], v[242:245], v[72:75]
	v_mfma_f32_16x16x32_bf16 v[64:67], v[174:177], v[242:245], v[64:67]
	v_mfma_f32_16x16x32_bf16 v[60:63], v[178:181], v[242:245], v[60:63]
	v_lshl_add_u64 v[152:153], v[130:131], 0, s[70:71]
	s_add_i32 m0, s56, 0xe000
	s_nop 0
	global_load_lds_dwordx4 v[152:153], off
	ds_read_b128 v[242:245], v250 offset:6144
	s_waitcnt lgkmcnt(7)
; __device__ __forceinline__ void gemm_stream256(f32x4 (&acc)[8][4], const Seg& cur, const Seg& nxt, bool has_next, bool first, int& st, unsigned char* lds, int tid) {
;     ...
;     for (int kt = 0; kt < nk; ++kt) {
;         const int idx = kt + 1;
;         const bool incur = idx < nk, doi = incur || has_next;
;         if (!late && doi) { if (incur) issue(apc, bpc, cur.lda, cur.ldb, idx * 64, s0 ^ 1); else issue(apn, bpn, nxt.lda, nxt.ldb, 0, s0 ^ 1); }
;         const unsigned char* As = lds + s0 * STAGE;
;         const unsigned char* Bs = As + 256 * 128;
; #pragma unroll
;         for (int ks = 0; ks < 2; ++ks) {
;             if (ks == 1 && late && doi) { if (incur) issue(apc, bpc, cur.lda, cur.ldb, idx * 64, s0 ^ 1); else issue(apn, bpn, nxt.lda, nxt.ldb, 0, s0 ^ 1); }
;             bf16x8 af[8], bfr[4];
;             const int co = ((ks * 4 + fq) ^ sz) * 16;
; #pragma unroll
;             for (int m = 0; m < 8; ++m) af[m] = *(const bf16x8*)(As + (wr * 128 + m * 16 + fr) * 128 + co);
; #pragma unroll
;             for (int n = 0; n < 4; ++n) bfr[n] = *(const bf16x8*)(Bs + (wc * 64 + n * 16 + fr) * 128 + co);
; #pragma unroll
;             for (int m = 0; m < 8; ++m)
; #pragma unroll
;                 for (int n = 0; n < 4; ++n) acc[m][n] = __builtin_amdgcn_mfma_f32_16x16x32_bf16(bfr[n], af[m], acc[m][n], 0, 0, 0);
;         }
;         asm volatile("s_waitcnt vmcnt(0) lgkmcnt(0)" ::: "memory");
;         __builtin_amdgcn_s_barrier();
;         asm volatile("" ::: "memory");
;         s0 ^= 1;
;     }
	v_mfma_f32_16x16x32_bf16 v[56:59], v[166:169], v[246:249], v[56:59]
	v_mfma_f32_16x16x32_bf16 v[52:55], v[170:173], v[246:249], v[52:55]
	v_mfma_f32_16x16x32_bf16 v[48:51], v[174:177], v[246:249], v[48:51]
	v_mfma_f32_16x16x32_bf16 v[44:47], v[178:181], v[246:249], v[44:47]
	ds_read_b128 v[246:249], v250 offset:8192
	s_waitcnt lgkmcnt(7)
	v_mfma_f32_16x16x32_bf16 v[40:43], v[166:169], v[182:185], v[40:43]
	v_mfma_f32_16x16x32_bf16 v[36:39], v[170:173], v[182:185], v[36:39]
	v_mfma_f32_16x16x32_bf16 v[32:35], v[174:177], v[182:185], v[32:35]
	v_mfma_f32_16x16x32_bf16 v[28:31], v[178:181], v[182:185], v[28:31]
	ds_read_b128 v[182:185], v250 offset:10240
	s_waitcnt lgkmcnt(7)
	v_mfma_f32_16x16x32_bf16 v[24:27], v[166:169], v[142:145], v[24:27]
	v_mfma_f32_16x16x32_bf16 v[20:23], v[170:173], v[142:145], v[20:23]
	v_mfma_f32_16x16x32_bf16 v[16:19], v[174:177], v[142:145], v[16:19]
	v_mfma_f32_16x16x32_bf16 v[12:15], v[178:181], v[142:145], v[12:15]
	ds_read_b128 v[142:145], v250 offset:12288
	s_waitcnt lgkmcnt(7)
	v_mfma_f32_16x16x32_bf16 v[8:11], v[166:169], v[146:149], v[8:11]
	v_mfma_f32_16x16x32_bf16 v[4:7], v[170:173], v[146:149], v[4:7]
	v_mfma_f32_16x16x32_bf16 v[0:3], v[174:177], v[146:149], v[0:3]
	v_mfma_f32_16x16x32_bf16 v[68:71], v[178:181], v[146:149], v[68:71]
	ds_read_b128 v[146:149], v250 offset:14336
	s_waitcnt lgkmcnt(7)
	v_mfma_f32_16x16x32_bf16 v[124:127], v[214:217], v[230:233], v[124:127]
	v_mfma_f32_16x16x32_bf16 v[120:123], v[218:221], v[230:233], v[120:123]
	v_mfma_f32_16x16x32_bf16 v[116:119], v[222:225], v[230:233], v[116:119]
	v_mfma_f32_16x16x32_bf16 v[112:115], v[226:229], v[230:233], v[112:115]
	s_waitcnt lgkmcnt(6)
	v_mfma_f32_16x16x32_bf16 v[108:111], v[214:217], v[234:237], v[108:111]
	v_mfma_f32_16x16x32_bf16 v[104:107], v[218:221], v[234:237], v[104:107]
	v_mfma_f32_16x16x32_bf16 v[100:103], v[222:225], v[234:237], v[100:103]
	v_mfma_f32_16x16x32_bf16 v[96:99], v[226:229], v[234:237], v[96:99]
	s_waitcnt lgkmcnt(5)
	v_mfma_f32_16x16x32_bf16 v[92:95], v[214:217], v[238:241], v[92:95]
	v_mfma_f32_16x16x32_bf16 v[88:91], v[218:221], v[238:241], v[88:91]
	v_mfma_f32_16x16x32_bf16 v[84:87], v[222:225], v[238:241], v[84:87]
	v_mfma_f32_16x16x32_bf16 v[80:83], v[226:229], v[238:241], v[80:83]
	s_waitcnt lgkmcnt(4)
	v_mfma_f32_16x16x32_bf16 v[76:79], v[214:217], v[242:245], v[76:79]
	v_mfma_f32_16x16x32_bf16 v[72:75], v[218:221], v[242:245], v[72:75]
	v_mfma_f32_16x16x32_bf16 v[64:67], v[222:225], v[242:245], v[64:67]
	v_mfma_f32_16x16x32_bf16 v[60:63], v[226:229], v[242:245], v[60:63]
	s_add_u32 s50, s50, 0x80
	s_cmpk_eq_i32 s50, 0x780
	s_cselect_b32 s50, 0, s50
	s_add_i32 s75, s75, 1
	s_xor_b32 s44, s44, 1
	s_waitcnt vmcnt(0) lgkmcnt(0)
	s_barrier
	s_cmpk_lg_i32 s75, 15
	s_cbranch_scc1 .Lp1_kloop
	v_mfma_f32_16x16x32_bf16 v[56:59], v[214:217], v[246:249], v[56:59]
	v_mfma_f32_16x16x32_bf16 v[52:55], v[218:221], v[246:249], v[52:55]
	v_mfma_f32_16x16x32_bf16 v[48:51], v[222:225], v[246:249], v[48:51]
	v_mfma_f32_16x16x32_bf16 v[44:47], v[226:229], v[246:249], v[44:47]
	v_mfma_f32_16x16x32_bf16 v[40:43], v[214:217], v[182:185], v[40:43]
	v_mfma_f32_16x16x32_bf16 v[36:39], v[218:221], v[182:185], v[36:39]
	v_mfma_f32_16x16x32_bf16 v[32:35], v[222:225], v[182:185], v[32:35]
	v_mfma_f32_16x16x32_bf16 v[28:31], v[226:229], v[182:185], v[28:31]
	v_mfma_f32_16x16x32_bf16 v[24:27], v[214:217], v[142:145], v[24:27]
	v_mfma_f32_16x16x32_bf16 v[20:23], v[218:221], v[142:145], v[20:23]
	v_mfma_f32_16x16x32_bf16 v[16:19], v[222:225], v[142:145], v[16:19]
	v_mfma_f32_16x16x32_bf16 v[12:15], v[226:229], v[142:145], v[12:15]
	v_mfma_f32_16x16x32_bf16 v[8:11], v[214:217], v[146:149], v[8:11]
	v_mfma_f32_16x16x32_bf16 v[4:7], v[218:221], v[146:149], v[4:7]
	v_mfma_f32_16x16x32_bf16 v[0:3], v[222:225], v[146:149], v[0:3]
	v_mfma_f32_16x16x32_bf16 v[68:71], v[226:229], v[146:149], v[68:71]
	s_mov_b32 s43, s44
	s_xor_b32 s44, s44, 1
	s_setprio 0

; __device__ __forceinline__ void gemm_stream256(f32x4 (&acc)[8][4], const Seg& cur, const Seg& nxt, bool has_next, bool first, int& st, unsigned char* lds, int tid) {
;     ...
;     for (int kt = 0; kt < nk; ++kt) {
;         const int idx = kt + 1;
;         const bool incur = idx < nk, doi = incur || has_next;
;         if (!late && doi) { if (incur) issue(apc, bpc, cur.lda, cur.ldb, idx * 64, s0 ^ 1); else issue(apn, bpn, nxt.lda, nxt.ldb, 0, s0 ^ 1); }
;         const unsigned char* As = lds + s0 * STAGE;
;         const unsigned char* Bs = As + 256 * 128;
; #pragma unroll
;         for (int ks = 0; ks < 2; ++ks) {
;             if (ks == 1 && late && doi) { if (incur) issue(apc, bpc, cur.lda, cur.ldb, idx * 64, s0 ^ 1); else issue(apn, bpn, nxt.lda, nxt.ldb, 0, s0 ^ 1); }
;             bf16x8 af[8], bfr[4];
;             const int co = ((ks * 4 + fq) ^ sz) * 16;
; #pragma unroll
;             for (int m = 0; m < 8; ++m) af[m] = *(const bf16x8*)(As + (wr * 128 + m * 16 + fr) * 128 + co);
; #pragma unroll
;             for (int n = 0; n < 4; ++n) bfr[n] = *(const bf16x8*)(Bs + (wc * 64 + n * 16 + fr) * 128 + co);
; #pragma unroll
;             for (int m = 0; m < 8; ++m)
; #pragma unroll
;                 for (int n = 0; n < 4; ++n) acc[m][n] = __builtin_amdgcn_mfma_f32_16x16x32_bf16(bfr[n], af[m], acc[m][n], 0, 0, 0);
;         }
;         asm volatile("s_waitcnt vmcnt(0) lgkmcnt(0)" ::: "memory");
;         __builtin_amdgcn_s_barrier();
;         asm volatile("" ::: "memory");
;         s0 ^= 1;
;     }
.LBB0_1030:
	s_lshr_b32 s86, s52, 3
	s_and_b32 s86, s86, 15
	s_lshl_b32 s86, s86, 7
	s_cmpk_eq_i32 s86, 0x780
	s_cselect_b32 s86, 0, s86
	s_mov_b32 s87, 0
	s_mov_b32 s75, 0
	s_and_b64 vcc, exec, s[76:77]
	s_cbranch_vccz .Lp7_kloop_np
	s_setprio 1
.Lp7_kloop_np:
	s_lshl_b32 s54, s41, 16
	s_xor_b32 s57, s54, 0x10000
	s_add_i32 s56, s49, s57
	v_add3_u32 v160, s54, v187, v191
	v_add3_u32 v133, s54, v187, v190
	v_add3_u32 v251, s54, v188, v191
	v_add3_u32 v250, s54, v188, v190
	ds_read_b128 v[166:169], v160 offset:32768
	ds_read_b128 v[170:173], v160 offset:34816
	ds_read_b128 v[174:177], v160 offset:36864
	ds_read_b128 v[152:155], v160 offset:38912
	ds_read_b128 v[230:233], v133
	ds_read_b128 v[234:237], v133 offset:2048
	ds_read_b128 v[238:241], v133 offset:4096
	ds_read_b128 v[242:245], v133 offset:6144
	v_lshl_add_u64 v[128:129], v[136:137], 0, s[86:87]
	v_lshl_add_u64 v[130:131], v[138:139], 0, s[86:87]
	v_lshl_add_u64 v[148:149], v[128:129], 0, s[94:95]
	s_mov_b32 m0, s56
	s_nop 0
	global_load_lds_dwordx4 v[148:149], off
	v_lshl_add_u64 v[150:151], v[128:129], 0, s[14:15]
	s_add_i32 m0, s56, 0x2000
	s_nop 0
	global_load_lds_dwordx4 v[150:151], off
	v_lshl_add_u64 v[148:149], v[128:129], 0, s[96:97]
	s_add_i32 m0, s56, 0x4000
	s_nop 0
	global_load_lds_dwordx4 v[148:149], off
	v_lshl_add_u64 v[150:151], v[128:129], 0, s[12:13]
	s_add_i32 m0, s56, 0x6000
	s_nop 0
	global_load_lds_dwordx4 v[150:151], off
	ds_read_b128 v[214:217], v251 offset:32768
	ds_read_b128 v[218:221], v251 offset:34816
	ds_read_b128 v[222:225], v251 offset:36864
	ds_read_b128 v[226:229], v251 offset:38912
	s_waitcnt lgkmcnt(11)
	ds_read_b128 v[246:249], v133 offset:8192
	s_waitcnt lgkmcnt(11)
	ds_read_b128 v[156:159], v133 offset:10240
	s_waitcnt lgkmcnt(11)
	ds_read_b128 v[140:143], v133 offset:12288
	s_waitcnt lgkmcnt(11)
	ds_read_b128 v[144:147], v133 offset:14336
	s_waitcnt lgkmcnt(11)
	v_mfma_f32_16x16x32_bf16 v[124:127], v[166:169], v[230:233], v[124:127]
	v_mfma_f32_16x16x32_bf16 v[120:123], v[170:173], v[230:233], v[120:123]
	v_mfma_f32_16x16x32_bf16 v[116:119], v[174:177], v[230:233], v[116:119]
	v_mfma_f32_16x16x32_bf16 v[112:115], v[152:155], v[230:233], v[112:115]
	s_mov_b64 s[70:71], 0x1452080
	v_lshl_add_u64 v[148:149], v[130:131], 0, s[70:71]
	s_add_i32 m0, s56, 0x8000
	s_nop 0
	global_load_lds_dwordx4 v[148:149], off
	ds_read_b128 v[230:233], v250
	s_waitcnt lgkmcnt(11)
	v_mfma_f32_16x16x32_bf16 v[108:111], v[166:169], v[234:237], v[108:111]
	v_mfma_f32_16x16x32_bf16 v[104:107], v[170:173], v[234:237], v[104:107]
	v_mfma_f32_16x16x32_bf16 v[100:103], v[174:177], v[234:237], v[100:103]
	v_mfma_f32_16x16x32_bf16 v[96:99], v[152:155], v[234:237], v[96:99]
	s_mov_b64 s[70:71], 0x1472080
	v_lshl_add_u64 v[150:151], v[130:131], 0, s[70:71]
	s_add_i32 m0, s56, 0xa000
	s_nop 0
	global_load_lds_dwordx4 v[150:151], off
	ds_read_b128 v[234:237], v250 offset:2048
	s_waitcnt lgkmcnt(11)
	v_mfma_f32_16x16x32_bf16 v[92:95], v[166:169], v[238:241], v[92:95]
	v_mfma_f32_16x16x32_bf16 v[88:91], v[170:173], v[238:241], v[88:91]
	v_mfma_f32_16x16x32_bf16 v[84:87], v[174:177], v[238:241], v[84:87]
	v_mfma_f32_16x16x32_bf16 v[80:83], v[152:155], v[238:241], v[80:83]
	s_mov_b64 s[70:71], 0x1492080
	v_lshl_add_u64 v[148:149], v[130:131], 0, s[70:71]
	s_add_i32 m0, s56, 0xc000
	s_nop 0
	global_load_lds_dwordx4 v[148:149], off
	ds_read_b128 v[238:241], v250 offset:4096
	s_waitcnt lgkmcnt(11)
	v_mfma_f32_16x16x32_bf16 v[76:79], v[166:169], v[242:245], v[76:79]
	v_mfma_f32_16x16x32_bf16 v[72:75], v[170:173], v[242:245], v[72:75]
	v_mfma_f32_16x16x32_bf16 v[64:67], v[174:177], v[242:245], v[64:67]
	v_mfma_f32_16x16x32_bf16 v[60:63], v[152:155], v[242:245], v[60:63]
	s_mov_b64 s[70:71], 0x14b2080
	v_lshl_add_u64 v[150:151], v[130:131], 0, s[70:71]
	s_add_i32 m0, s56, 0xe000
	s_nop 0
	global_load_lds_dwordx4 v[150:151], off
	ds_read_b128 v[242:245], v250 offset:6144
	s_waitcnt lgkmcnt(7)
	v_mfma_f32_16x16x32_bf16 v[56:59], v[166:169], v[246:249], v[56:59]
	v_mfma_f32_16x16x32_bf16 v[52:55], v[170:173], v[246:249], v[52:55]
	v_mfma_f32_16x16x32_bf16 v[48:51], v[174:177], v[246:249], v[48:51]
	v_mfma_f32_16x16x32_bf16 v[44:47], v[152:155], v[246:249], v[44:47]
	ds_read_b128 v[246:249], v250 offset:8192
	s_waitcnt lgkmcnt(7)
	v_mfma_f32_16x16x32_bf16 v[40:43], v[166:169], v[156:159], v[40:43]
	v_mfma_f32_16x16x32_bf16 v[36:39], v[170:173], v[156:159], v[36:39]
	v_mfma_f32_16x16x32_bf16 v[32:35], v[174:177], v[156:159], v[32:35]
	v_mfma_f32_16x16x32_bf16 v[28:31], v[152:155], v[156:159], v[28:31]
	ds_read_b128 v[156:159], v250 offset:10240
	s_waitcnt lgkmcnt(7)
	v_mfma_f32_16x16x32_bf16 v[24:27], v[166:169], v[140:143], v[24:27]
	v_mfma_f32_16x16x32_bf16 v[20:23], v[170:173], v[140:143], v[20:23]
	v_mfma_f32_16x16x32_bf16 v[16:19], v[174:177], v[140:143], v[16:19]
	v_mfma_f32_16x16x32_bf16 v[12:15], v[152:155], v[140:143], v[12:15]
	ds_read_b128 v[140:143], v250 offset:12288
	s_waitcnt lgkmcnt(7)
	v_mfma_f32_16x16x32_bf16 v[8:11], v[166:169], v[144:147], v[8:11]
	v_mfma_f32_16x16x32_bf16 v[4:7], v[170:173], v[144:147], v[4:7]
	v_mfma_f32_16x16x32_bf16 v[0:3], v[174:177], v[144:147], v[0:3]
	v_mfma_f32_16x16x32_bf16 v[68:71], v[152:155], v[144:147], v[68:71]
	ds_read_b128 v[144:147], v250 offset:14336
	s_waitcnt lgkmcnt(7)
	v_mfma_f32_16x16x32_bf16 v[124:127], v[214:217], v[230:233], v[124:127]
	v_mfma_f32_16x16x32_bf16 v[120:123], v[218:221], v[230:233], v[120:123]
	v_mfma_f32_16x16x32_bf16 v[116:119], v[222:225], v[230:233], v[116:119]
	v_mfma_f32_16x16x32_bf16 v[112:115], v[226:229], v[230:233], v[112:115]
	s_waitcnt lgkmcnt(6)
	v_mfma_f32_16x16x32_bf16 v[108:111], v[214:217], v[234:237], v[108:111]
	v_mfma_f32_16x16x32_bf16 v[104:107], v[218:221], v[234:237], v[104:107]
	v_mfma_f32_16x16x32_bf16 v[100:103], v[222:225], v[234:237], v[100:103]
	v_mfma_f32_16x16x32_bf16 v[96:99], v[226:229], v[234:237], v[96:99]
	s_waitcnt lgkmcnt(5)
	v_mfma_f32_16x16x32_bf16 v[92:95], v[214:217], v[238:241], v[92:95]
	v_mfma_f32_16x16x32_bf16 v[88:91], v[218:221], v[238:241], v[88:91]
	v_mfma_f32_16x16x32_bf16 v[84:87], v[222:225], v[238:241], v[84:87]
	v_mfma_f32_16x16x32_bf16 v[80:83], v[226:229], v[238:241], v[80:83]
	s_waitcnt lgkmcnt(4)
	v_mfma_f32_16x16x32_bf16 v[76:79], v[214:217], v[242:245], v[76:79]
	v_mfma_f32_16x16x32_bf16 v[72:75], v[218:221], v[242:245], v[72:75]
	v_mfma_f32_16x16x32_bf16 v[64:67], v[222:225], v[242:245], v[64:67]
	v_mfma_f32_16x16x32_bf16 v[60:63], v[226:229], v[242:245], v[60:63]
	s_add_u32 s86, s86, 0x80
	s_cmpk_eq_i32 s86, 0x780
	s_cselect_b32 s86, 0, s86
	s_add_i32 s75, s75, 1
	s_xor_b32 s41, s41, 1
	s_waitcnt vmcnt(0) lgkmcnt(0)
	s_barrier
; __device__ __forceinline__ void gemm_stream256(f32x4 (&acc)[8][4], const Seg& cur, const Seg& nxt, bool has_next, bool first, int& st, unsigned char* lds, int tid) {
;     ...
;     for (int kt = 0; kt < nk; ++kt) {
;         const int idx = kt + 1;
;         const bool incur = idx < nk, doi = incur || has_next;
;         if (!late && doi) { if (incur) issue(apc, bpc, cur.lda, cur.ldb, idx * 64, s0 ^ 1); else issue(apn, bpn, nxt.lda, nxt.ldb, 0, s0 ^ 1); }
;         const unsigned char* As = lds + s0 * STAGE;
;         const unsigned char* Bs = As + 256 * 128;
; #pragma unroll
;         for (int ks = 0; ks < 2; ++ks) {
;             if (ks == 1 && late && doi) { if (incur) issue(apc, bpc, cur.lda, cur.ldb, idx * 64, s0 ^ 1); else issue(apn, bpn, nxt.lda, nxt.ldb, 0, s0 ^ 1); }
;             bf16x8 af[8], bfr[4];
;             const int co = ((ks * 4 + fq) ^ sz) * 16;
; #pragma unroll
;             for (int m = 0; m < 8; ++m) af[m] = *(const bf16x8*)(As + (wr * 128 + m * 16 + fr) * 128 + co);
; #pragma unroll
;             for (int n = 0; n < 4; ++n) bfr[n] = *(const bf16x8*)(Bs + (wc * 64 + n * 16 + fr) * 128 + co);
; #pragma unroll
;             for (int m = 0; m < 8; ++m)
; #pragma unroll
;                 for (int n = 0; n < 4; ++n) acc[m][n] = __builtin_amdgcn_mfma_f32_16x16x32_bf16(bfr[n], af[m], acc[m][n], 0, 0, 0);
;         }
;         asm volatile("s_waitcnt vmcnt(0) lgkmcnt(0)" ::: "memory");
;         __builtin_amdgcn_s_barrier();
;         asm volatile("" ::: "memory");
;         s0 ^= 1;
;     }
.Lp7_kloop:
	s_lshl_b32 s54, s41, 16
	s_xor_b32 s57, s54, 0x10000
	s_add_i32 s56, s49, s57
	v_add3_u32 v160, s54, v187, v191
	v_add3_u32 v133, s54, v187, v190
	v_add3_u32 v251, s54, v188, v191
	v_add3_u32 v250, s54, v188, v190
	ds_read_b128 v[166:169], v160 offset:32768
	ds_read_b128 v[170:173], v160 offset:34816
	ds_read_b128 v[174:177], v160 offset:36864
	ds_read_b128 v[152:155], v160 offset:38912
	ds_read_b128 v[230:233], v133
	ds_read_b128 v[234:237], v133 offset:2048
	ds_read_b128 v[238:241], v133 offset:4096
	ds_read_b128 v[242:245], v133 offset:6144
	v_lshl_add_u64 v[128:129], v[136:137], 0, s[86:87]
	v_lshl_add_u64 v[130:131], v[138:139], 0, s[86:87]
	v_mfma_f32_16x16x32_bf16 v[56:59], v[214:217], v[246:249], v[56:59]
	v_mfma_f32_16x16x32_bf16 v[52:55], v[218:221], v[246:249], v[52:55]
	v_mfma_f32_16x16x32_bf16 v[48:51], v[222:225], v[246:249], v[48:51]
	v_mfma_f32_16x16x32_bf16 v[44:47], v[226:229], v[246:249], v[44:47]
	v_lshl_add_u64 v[148:149], v[128:129], 0, s[94:95]
	s_mov_b32 m0, s56
	s_nop 0
	global_load_lds_dwordx4 v[148:149], off
	v_mfma_f32_16x16x32_bf16 v[40:43], v[214:217], v[156:159], v[40:43]
	v_mfma_f32_16x16x32_bf16 v[36:39], v[218:221], v[156:159], v[36:39]
	v_mfma_f32_16x16x32_bf16 v[32:35], v[222:225], v[156:159], v[32:35]
	v_mfma_f32_16x16x32_bf16 v[28:31], v[226:229], v[156:159], v[28:31]
	v_lshl_add_u64 v[150:151], v[128:129], 0, s[14:15]
	s_add_i32 m0, s56, 0x2000
	s_nop 0
	global_load_lds_dwordx4 v[150:151], off
	v_mfma_f32_16x16x32_bf16 v[24:27], v[214:217], v[140:143], v[24:27]
	v_mfma_f32_16x16x32_bf16 v[20:23], v[218:221], v[140:143], v[20:23]
	v_mfma_f32_16x16x32_bf16 v[16:19], v[222:225], v[140:143], v[16:19]
	v_mfma_f32_16x16x32_bf16 v[12:15], v[226:229], v[140:143], v[12:15]
	v_lshl_add_u64 v[148:149], v[128:129], 0, s[96:97]
	s_add_i32 m0, s56, 0x4000
	s_nop 0
	global_load_lds_dwordx4 v[148:149], off
	v_mfma_f32_16x16x32_bf16 v[8:11], v[214:217], v[144:147], v[8:11]
	v_mfma_f32_16x16x32_bf16 v[4:7], v[218:221], v[144:147], v[4:7]
	v_mfma_f32_16x16x32_bf16 v[0:3], v[222:225], v[144:147], v[0:3]
	v_mfma_f32_16x16x32_bf16 v[68:71], v[226:229], v[144:147], v[68:71]
	v_lshl_add_u64 v[150:151], v[128:129], 0, s[12:13]
	s_add_i32 m0, s56, 0x6000
	s_nop 0
	global_load_lds_dwordx4 v[150:151], off
	s_waitcnt lgkmcnt(0)
	ds_read_b128 v[214:217], v251 offset:32768
	ds_read_b128 v[218:221], v251 offset:34816
	ds_read_b128 v[222:225], v251 offset:36864
	ds_read_b128 v[226:229], v251 offset:38912
	ds_read_b128 v[246:249], v133 offset:8192
	ds_read_b128 v[156:159], v133 offset:10240
	ds_read_b128 v[140:143], v133 offset:12288
	ds_read_b128 v[144:147], v133 offset:14336
	v_mfma_f32_16x16x32_bf16 v[124:127], v[166:169], v[230:233], v[124:127]
	v_mfma_f32_16x16x32_bf16 v[120:123], v[170:173], v[230:233], v[120:123]
	v_mfma_f32_16x16x32_bf16 v[116:119], v[174:177], v[230:233], v[116:119]
	v_mfma_f32_16x16x32_bf16 v[112:115], v[152:155], v[230:233], v[112:115]
	s_mov_b64 s[70:71], 0x1452080
	v_lshl_add_u64 v[148:149], v[130:131], 0, s[70:71]
	s_add_i32 m0, s56, 0x8000
	s_nop 0
	global_load_lds_dwordx4 v[148:149], off
	ds_read_b128 v[230:233], v250
	v_mfma_f32_16x16x32_bf16 v[108:111], v[166:169], v[234:237], v[108:111]
	v_mfma_f32_16x16x32_bf16 v[104:107], v[170:173], v[234:237], v[104:107]
	v_mfma_f32_16x16x32_bf16 v[100:103], v[174:177], v[234:237], v[100:103]
	v_mfma_f32_16x16x32_bf16 v[96:99], v[152:155], v[234:237], v[96:99]
	s_mov_b64 s[70:71], 0x1472080
	v_lshl_add_u64 v[150:151], v[130:131], 0, s[70:71]
	s_add_i32 m0, s56, 0xa000
	s_nop 0
	global_load_lds_dwordx4 v[150:151], off
	ds_read_b128 v[234:237], v250 offset:2048
	v_mfma_f32_16x16x32_bf16 v[92:95], v[166:169], v[238:241], v[92:95]
	v_mfma_f32_16x16x32_bf16 v[88:91], v[170:173], v[238:241], v[88:91]
	v_mfma_f32_16x16x32_bf16 v[84:87], v[174:177], v[238:241], v[84:87]
	v_mfma_f32_16x16x32_bf16 v[80:83], v[152:155], v[238:241], v[80:83]
	s_mov_b64 s[70:71], 0x1492080
	v_lshl_add_u64 v[148:149], v[130:131], 0, s[70:71]
	s_add_i32 m0, s56, 0xc000
	s_nop 0
	global_load_lds_dwordx4 v[148:149], off
	ds_read_b128 v[238:241], v250 offset:4096
	v_mfma_f32_16x16x32_bf16 v[76:79], v[166:169], v[242:245], v[76:79]
	v_mfma_f32_16x16x32_bf16 v[72:75], v[170:173], v[242:245], v[72:75]
	v_mfma_f32_16x16x32_bf16 v[64:67], v[174:177], v[242:245], v[64:67]
	v_mfma_f32_16x16x32_bf16 v[60:63], v[152:155], v[242:245], v[60:63]
	s_mov_b64 s[70:71], 0x14b2080
	v_lshl_add_u64 v[150:151], v[130:131], 0, s[70:71]
	s_add_i32 m0, s56, 0xe000
	s_nop 0
	global_load_lds_dwordx4 v[150:151], off
	ds_read_b128 v[242:245], v250 offset:6144
	s_waitcnt lgkmcnt(7)
; __device__ __forceinline__ void gemm_stream256(f32x4 (&acc)[8][4], const Seg& cur, const Seg& nxt, bool has_next, bool first, int& st, unsigned char* lds, int tid) {
;     ...
;     for (int kt = 0; kt < nk; ++kt) {
;         const int idx = kt + 1;
;         const bool incur = idx < nk, doi = incur || has_next;
;         if (!late && doi) { if (incur) issue(apc, bpc, cur.lda, cur.ldb, idx * 64, s0 ^ 1); else issue(apn, bpn, nxt.lda, nxt.ldb, 0, s0 ^ 1); }
;         const unsigned char* As = lds + s0 * STAGE;
;         const unsigned char* Bs = As + 256 * 128;
; #pragma unroll
;         for (int ks = 0; ks < 2; ++ks) {
;             if (ks == 1 && late && doi) { if (incur) issue(apc, bpc, cur.lda, cur.ldb, idx * 64, s0 ^ 1); else issue(apn, bpn, nxt.lda, nxt.ldb, 0, s0 ^ 1); }
;             bf16x8 af[8], bfr[4];
;             const int co = ((ks * 4 + fq) ^ sz) * 16;
; #pragma unroll
;             for (int m = 0; m < 8; ++m) af[m] = *(const bf16x8*)(As + (wr * 128 + m * 16 + fr) * 128 + co);
; #pragma unroll
;             for (int n = 0; n < 4; ++n) bfr[n] = *(const bf16x8*)(Bs + (wc * 64 + n * 16 + fr) * 128 + co);
; #pragma unroll
;             for (int m = 0; m < 8; ++m)
; #pragma unroll
;                 for (int n = 0; n < 4; ++n) acc[m][n] = __builtin_amdgcn_mfma_f32_16x16x32_bf16(bfr[n], af[m], acc[m][n], 0, 0, 0);
;         }
;         asm volatile("s_waitcnt vmcnt(0) lgkmcnt(0)" ::: "memory");
;         __builtin_amdgcn_s_barrier();
;         asm volatile("" ::: "memory");
;         s0 ^= 1;
;     }
	v_mfma_f32_16x16x32_bf16 v[56:59], v[166:169], v[246:249], v[56:59]
	v_mfma_f32_16x16x32_bf16 v[52:55], v[170:173], v[246:249], v[52:55]
	v_mfma_f32_16x16x32_bf16 v[48:51], v[174:177], v[246:249], v[48:51]
	v_mfma_f32_16x16x32_bf16 v[44:47], v[152:155], v[246:249], v[44:47]
	ds_read_b128 v[246:249], v250 offset:8192
	s_waitcnt lgkmcnt(7)
	v_mfma_f32_16x16x32_bf16 v[40:43], v[166:169], v[156:159], v[40:43]
	v_mfma_f32_16x16x32_bf16 v[36:39], v[170:173], v[156:159], v[36:39]
	v_mfma_f32_16x16x32_bf16 v[32:35], v[174:177], v[156:159], v[32:35]
	v_mfma_f32_16x16x32_bf16 v[28:31], v[152:155], v[156:159], v[28:31]
	ds_read_b128 v[156:159], v250 offset:10240
	s_waitcnt lgkmcnt(7)
	v_mfma_f32_16x16x32_bf16 v[24:27], v[166:169], v[140:143], v[24:27]
	v_mfma_f32_16x16x32_bf16 v[20:23], v[170:173], v[140:143], v[20:23]
	v_mfma_f32_16x16x32_bf16 v[16:19], v[174:177], v[140:143], v[16:19]
	v_mfma_f32_16x16x32_bf16 v[12:15], v[152:155], v[140:143], v[12:15]
	ds_read_b128 v[140:143], v250 offset:12288
	s_waitcnt lgkmcnt(7)
	v_mfma_f32_16x16x32_bf16 v[8:11], v[166:169], v[144:147], v[8:11]
	v_mfma_f32_16x16x32_bf16 v[4:7], v[170:173], v[144:147], v[4:7]
	v_mfma_f32_16x16x32_bf16 v[0:3], v[174:177], v[144:147], v[0:3]
	v_mfma_f32_16x16x32_bf16 v[68:71], v[152:155], v[144:147], v[68:71]
	ds_read_b128 v[144:147], v250 offset:14336
	s_waitcnt lgkmcnt(7)
	v_mfma_f32_16x16x32_bf16 v[124:127], v[214:217], v[230:233], v[124:127]
	v_mfma_f32_16x16x32_bf16 v[120:123], v[218:221], v[230:233], v[120:123]
	v_mfma_f32_16x16x32_bf16 v[116:119], v[222:225], v[230:233], v[116:119]
	v_mfma_f32_16x16x32_bf16 v[112:115], v[226:229], v[230:233], v[112:115]
	s_waitcnt lgkmcnt(6)
	v_mfma_f32_16x16x32_bf16 v[108:111], v[214:217], v[234:237], v[108:111]
	v_mfma_f32_16x16x32_bf16 v[104:107], v[218:221], v[234:237], v[104:107]
	v_mfma_f32_16x16x32_bf16 v[100:103], v[222:225], v[234:237], v[100:103]
	v_mfma_f32_16x16x32_bf16 v[96:99], v[226:229], v[234:237], v[96:99]
	s_waitcnt lgkmcnt(5)
	v_mfma_f32_16x16x32_bf16 v[92:95], v[214:217], v[238:241], v[92:95]
	v_mfma_f32_16x16x32_bf16 v[88:91], v[218:221], v[238:241], v[88:91]
	v_mfma_f32_16x16x32_bf16 v[84:87], v[222:225], v[238:241], v[84:87]
	v_mfma_f32_16x16x32_bf16 v[80:83], v[226:229], v[238:241], v[80:83]
	s_waitcnt lgkmcnt(4)
	v_mfma_f32_16x16x32_bf16 v[76:79], v[214:217], v[242:245], v[76:79]
	v_mfma_f32_16x16x32_bf16 v[72:75], v[218:221], v[242:245], v[72:75]
	v_mfma_f32_16x16x32_bf16 v[64:67], v[222:225], v[242:245], v[64:67]
	v_mfma_f32_16x16x32_bf16 v[60:63], v[226:229], v[242:245], v[60:63]
	s_add_u32 s86, s86, 0x80
	s_cmpk_eq_i32 s86, 0x780
	s_cselect_b32 s86, 0, s86
	s_add_i32 s75, s75, 1
	s_xor_b32 s41, s41, 1
	s_waitcnt vmcnt(0) lgkmcnt(0)
	s_barrier
	s_cmpk_lg_i32 s75, 15
	s_cbranch_scc1 .Lp7_kloop
	v_mfma_f32_16x16x32_bf16 v[56:59], v[214:217], v[246:249], v[56:59]
	v_mfma_f32_16x16x32_bf16 v[52:55], v[218:221], v[246:249], v[52:55]
	v_mfma_f32_16x16x32_bf16 v[48:51], v[222:225], v[246:249], v[48:51]
	v_mfma_f32_16x16x32_bf16 v[44:47], v[226:229], v[246:249], v[44:47]
	v_mfma_f32_16x16x32_bf16 v[40:43], v[214:217], v[156:159], v[40:43]
	v_mfma_f32_16x16x32_bf16 v[36:39], v[218:221], v[156:159], v[36:39]
	v_mfma_f32_16x16x32_bf16 v[32:35], v[222:225], v[156:159], v[32:35]
	v_mfma_f32_16x16x32_bf16 v[28:31], v[226:229], v[156:159], v[28:31]
	v_mfma_f32_16x16x32_bf16 v[24:27], v[214:217], v[140:143], v[24:27]
	v_mfma_f32_16x16x32_bf16 v[20:23], v[218:221], v[140:143], v[20:23]
	v_mfma_f32_16x16x32_bf16 v[16:19], v[222:225], v[140:143], v[16:19]
	v_mfma_f32_16x16x32_bf16 v[12:15], v[226:229], v[140:143], v[12:15]
	v_mfma_f32_16x16x32_bf16 v[8:11], v[214:217], v[144:147], v[8:11]
	v_mfma_f32_16x16x32_bf16 v[4:7], v[218:221], v[144:147], v[4:7]
	v_mfma_f32_16x16x32_bf16 v[0:3], v[222:225], v[144:147], v[0:3]
	v_mfma_f32_16x16x32_bf16 v[68:71], v[226:229], v[144:147], v[68:71]
	s_mov_b32 s2, s41
	s_xor_b32 s41, s41, 1
	s_setprio 0
	s_branch .LBB0_1041

; __device__ __forceinline__ void gemm_stream256(f32x4 (&acc)[8][4], const Seg& cur, const Seg& nxt, bool has_next, bool first, int& st, unsigned char* lds, int tid) {
;     ...
;     for (int kt = 0; kt < nk; ++kt) {
;         const int idx = kt + 1;
;         const bool incur = idx < nk, doi = incur || has_next;
;         if (!late && doi) { if (incur) issue(apc, bpc, cur.lda, cur.ldb, idx * 64, s0 ^ 1); else issue(apn, bpn, nxt.lda, nxt.ldb, 0, s0 ^ 1); }
;         const unsigned char* As = lds + s0 * STAGE;
;         const unsigned char* Bs = As + 256 * 128;
; #pragma unroll
;         for (int ks = 0; ks < 2; ++ks) {
;             if (ks == 1 && late && doi) { if (incur) issue(apc, bpc, cur.lda, cur.ldb, idx * 64, s0 ^ 1); else issue(apn, bpn, nxt.lda, nxt.ldb, 0, s0 ^ 1); }
;             bf16x8 af[8], bfr[4];
;             const int co = ((ks * 4 + fq) ^ sz) * 16;
; #pragma unroll
;             for (int m = 0; m < 8; ++m) af[m] = *(const bf16x8*)(As + (wr * 128 + m * 16 + fr) * 128 + co);
; #pragma unroll
;             for (int n = 0; n < 4; ++n) bfr[n] = *(const bf16x8*)(Bs + (wc * 64 + n * 16 + fr) * 128 + co);
; #pragma unroll
;             for (int m = 0; m < 8; ++m)
; #pragma unroll
;                 for (int n = 0; n < 4; ++n) acc[m][n] = __builtin_amdgcn_mfma_f32_16x16x32_bf16(bfr[n], af[m], acc[m][n], 0, 0, 0);
;         }
;         asm volatile("s_waitcnt vmcnt(0) lgkmcnt(0)" ::: "memory");
;         __builtin_amdgcn_s_barrier();
;         asm volatile("" ::: "memory");
;         s0 ^= 1;
;     }
.LBB0_1079:
.LBB0_1078:
	v_readlane_b32 s78, v253, 0
	s_lshr_b32 s86, s78, 3
	s_and_b32 s86, s86, 15
	s_lshl_b32 s86, s86, 7
	s_mov_b32 s87, 0
	s_mov_b32 s90, 0
	s_and_b64 vcc, exec, s[76:77]
	s_cbranch_vccz .Lp8_kloop_np
	s_setprio 1
.Lp8_kloop_np:
	s_lshl_b32 s2, s75, 16
	s_xor_b32 s91, s2, 0x10000
	s_add_i32 s91, s71, s91
	v_add3_u32 v179, s2, v174, v178
	v_add3_u32 v160, s2, v174, v177
	v_add3_u32 v251, s2, v175, v178
	v_add3_u32 v250, s2, v175, v177
	ds_read_b128 v[180:183], v179 offset:32768
	ds_read_b128 v[184:187], v179 offset:34816
	ds_read_b128 v[188:191], v179 offset:36864
	ds_read_b128 v[192:195], v179 offset:38912
	ds_read_b128 v[230:233], v160
	ds_read_b128 v[234:237], v160 offset:2048
	ds_read_b128 v[238:241], v160 offset:4096
	ds_read_b128 v[242:245], v160 offset:6144
	v_lshl_add_u64 v[128:129], v[150:151], 0, s[86:87]
	v_lshl_add_u64 v[130:131], v[148:149], 0, s[86:87]
	s_mov_b64 s[80:81], 0x669b080
	v_lshl_add_u64 v[162:163], v[128:129], 0, s[80:81]
	s_mov_b32 m0, s91
	s_nop 0
	global_load_lds_dwordx4 v[162:163], off
	s_mov_b64 s[80:81], 0x66f3080
	v_lshl_add_u64 v[164:165], v[128:129], 0, s[80:81]
	s_add_i32 m0, s91, 0x2000
	s_nop 0
	global_load_lds_dwordx4 v[164:165], off
	s_mov_b64 s[80:81], 0x674b080
	v_lshl_add_u64 v[162:163], v[128:129], 0, s[80:81]
	s_add_i32 m0, s91, 0x4000
	s_nop 0
	global_load_lds_dwordx4 v[162:163], off
	s_mov_b64 s[80:81], 0x67a3080
	v_lshl_add_u64 v[164:165], v[128:129], 0, s[80:81]
	s_add_i32 m0, s91, 0x6000
	s_nop 0
	global_load_lds_dwordx4 v[164:165], off
	ds_read_b128 v[214:217], v251 offset:32768
	ds_read_b128 v[218:221], v251 offset:34816
	ds_read_b128 v[222:225], v251 offset:36864
	ds_read_b128 v[226:229], v251 offset:38912
	s_waitcnt lgkmcnt(11)
	ds_read_b128 v[246:249], v160 offset:8192
	s_waitcnt lgkmcnt(11)
	ds_read_b128 v[196:199], v160 offset:10240
	s_waitcnt lgkmcnt(11)
	ds_read_b128 v[152:155], v160 offset:12288
	s_waitcnt lgkmcnt(11)
	ds_read_b128 v[156:159], v160 offset:14336
	s_waitcnt lgkmcnt(11)
	v_mfma_f32_16x16x32_bf16 v[124:127], v[180:183], v[230:233], v[124:127]
	v_mfma_f32_16x16x32_bf16 v[120:123], v[184:187], v[230:233], v[120:123]
	v_mfma_f32_16x16x32_bf16 v[116:119], v[188:191], v[230:233], v[116:119]
	v_mfma_f32_16x16x32_bf16 v[112:115], v[192:195], v[230:233], v[112:115]
	s_mov_b64 s[80:81], 0x1f52080
	v_lshl_add_u64 v[162:163], v[130:131], 0, s[80:81]
	s_add_i32 m0, s91, 0x8000
	s_nop 0
	global_load_lds_dwordx4 v[162:163], off
	ds_read_b128 v[230:233], v250
	s_waitcnt lgkmcnt(11)
	v_mfma_f32_16x16x32_bf16 v[108:111], v[180:183], v[234:237], v[108:111]
	v_mfma_f32_16x16x32_bf16 v[104:107], v[184:187], v[234:237], v[104:107]
	v_mfma_f32_16x16x32_bf16 v[100:103], v[188:191], v[234:237], v[100:103]
	v_mfma_f32_16x16x32_bf16 v[96:99], v[192:195], v[234:237], v[96:99]
	s_mov_b64 s[80:81], 0x1faa080
	v_lshl_add_u64 v[164:165], v[130:131], 0, s[80:81]
	s_add_i32 m0, s91, 0xa000
	s_nop 0
	global_load_lds_dwordx4 v[164:165], off
	ds_read_b128 v[234:237], v250 offset:2048
	s_waitcnt lgkmcnt(11)
	v_mfma_f32_16x16x32_bf16 v[92:95], v[180:183], v[238:241], v[92:95]
	v_mfma_f32_16x16x32_bf16 v[88:91], v[184:187], v[238:241], v[88:91]
	v_mfma_f32_16x16x32_bf16 v[84:87], v[188:191], v[238:241], v[84:87]
	v_mfma_f32_16x16x32_bf16 v[80:83], v[192:195], v[238:241], v[80:83]
	s_mov_b64 s[80:81], 0x2002080
	v_lshl_add_u64 v[162:163], v[130:131], 0, s[80:81]
	s_add_i32 m0, s91, 0xc000
	s_nop 0
	global_load_lds_dwordx4 v[162:163], off
	ds_read_b128 v[238:241], v250 offset:4096
	s_waitcnt lgkmcnt(11)
	v_mfma_f32_16x16x32_bf16 v[76:79], v[180:183], v[242:245], v[76:79]
	v_mfma_f32_16x16x32_bf16 v[72:75], v[184:187], v[242:245], v[72:75]
	v_mfma_f32_16x16x32_bf16 v[68:71], v[188:191], v[242:245], v[68:71]
	v_mfma_f32_16x16x32_bf16 v[64:67], v[192:195], v[242:245], v[64:67]
	s_mov_b64 s[80:81], 0x205a080
	v_lshl_add_u64 v[164:165], v[130:131], 0, s[80:81]
	s_add_i32 m0, s91, 0xe000
	s_nop 0
	global_load_lds_dwordx4 v[164:165], off
	ds_read_b128 v[242:245], v250 offset:6144
	s_waitcnt lgkmcnt(7)
	v_mfma_f32_16x16x32_bf16 v[60:63], v[180:183], v[246:249], v[60:63]
	v_mfma_f32_16x16x32_bf16 v[56:59], v[184:187], v[246:249], v[56:59]
	v_mfma_f32_16x16x32_bf16 v[52:55], v[188:191], v[246:249], v[52:55]
	v_mfma_f32_16x16x32_bf16 v[48:51], v[192:195], v[246:249], v[48:51]
	ds_read_b128 v[246:249], v250 offset:8192
	s_waitcnt lgkmcnt(7)
	v_mfma_f32_16x16x32_bf16 v[44:47], v[180:183], v[196:199], v[44:47]
	v_mfma_f32_16x16x32_bf16 v[40:43], v[184:187], v[196:199], v[40:43]
	v_mfma_f32_16x16x32_bf16 v[36:39], v[188:191], v[196:199], v[36:39]
	v_mfma_f32_16x16x32_bf16 v[32:35], v[192:195], v[196:199], v[32:35]
	ds_read_b128 v[196:199], v250 offset:10240
	s_waitcnt lgkmcnt(7)
	v_mfma_f32_16x16x32_bf16 v[28:31], v[180:183], v[152:155], v[28:31]
	v_mfma_f32_16x16x32_bf16 v[24:27], v[184:187], v[152:155], v[24:27]
	v_mfma_f32_16x16x32_bf16 v[20:23], v[188:191], v[152:155], v[20:23]
	v_mfma_f32_16x16x32_bf16 v[16:19], v[192:195], v[152:155], v[16:19]
	ds_read_b128 v[152:155], v250 offset:12288
	s_waitcnt lgkmcnt(7)
	v_mfma_f32_16x16x32_bf16 v[12:15], v[180:183], v[156:159], v[12:15]
	v_mfma_f32_16x16x32_bf16 v[4:7], v[184:187], v[156:159], v[4:7]
	v_mfma_f32_16x16x32_bf16 v[0:3], v[188:191], v[156:159], v[0:3]
	v_mfma_f32_16x16x32_bf16 v[8:11], v[192:195], v[156:159], v[8:11]
	ds_read_b128 v[156:159], v250 offset:14336
	s_waitcnt lgkmcnt(7)
	v_mfma_f32_16x16x32_bf16 v[124:127], v[214:217], v[230:233], v[124:127]
	v_mfma_f32_16x16x32_bf16 v[120:123], v[218:221], v[230:233], v[120:123]
	v_mfma_f32_16x16x32_bf16 v[116:119], v[222:225], v[230:233], v[116:119]
	v_mfma_f32_16x16x32_bf16 v[112:115], v[226:229], v[230:233], v[112:115]
	s_waitcnt lgkmcnt(6)
	v_mfma_f32_16x16x32_bf16 v[108:111], v[214:217], v[234:237], v[108:111]
	v_mfma_f32_16x16x32_bf16 v[104:107], v[218:221], v[234:237], v[104:107]
	v_mfma_f32_16x16x32_bf16 v[100:103], v[222:225], v[234:237], v[100:103]
	v_mfma_f32_16x16x32_bf16 v[96:99], v[226:229], v[234:237], v[96:99]
	s_waitcnt lgkmcnt(5)
	v_mfma_f32_16x16x32_bf16 v[92:95], v[214:217], v[238:241], v[92:95]
	v_mfma_f32_16x16x32_bf16 v[88:91], v[218:221], v[238:241], v[88:91]
	v_mfma_f32_16x16x32_bf16 v[84:87], v[222:225], v[238:241], v[84:87]
	v_mfma_f32_16x16x32_bf16 v[80:83], v[226:229], v[238:241], v[80:83]
	s_waitcnt lgkmcnt(4)
	v_mfma_f32_16x16x32_bf16 v[76:79], v[214:217], v[242:245], v[76:79]
	v_mfma_f32_16x16x32_bf16 v[72:75], v[218:221], v[242:245], v[72:75]
	v_mfma_f32_16x16x32_bf16 v[68:71], v[222:225], v[242:245], v[68:71]
	v_mfma_f32_16x16x32_bf16 v[64:67], v[226:229], v[242:245], v[64:67]
	s_add_u32 s86, s86, 0x80
	s_cmpk_eq_i32 s86, 0x1580
	s_cselect_b32 s86, 0, s86
	s_add_i32 s90, s90, 1
	s_xor_b32 s75, s75, 1
	s_waitcnt vmcnt(0) lgkmcnt(0)
	s_barrier
; __device__ __forceinline__ void gemm_stream256(f32x4 (&acc)[8][4], const Seg& cur, const Seg& nxt, bool has_next, bool first, int& st, unsigned char* lds, int tid) {
;     ...
;     for (int kt = 0; kt < nk; ++kt) {
;         const int idx = kt + 1;
;         const bool incur = idx < nk, doi = incur || has_next;
;         if (!late && doi) { if (incur) issue(apc, bpc, cur.lda, cur.ldb, idx * 64, s0 ^ 1); else issue(apn, bpn, nxt.lda, nxt.ldb, 0, s0 ^ 1); }
;         const unsigned char* As = lds + s0 * STAGE;
;         const unsigned char* Bs = As + 256 * 128;
; #pragma unroll
;         for (int ks = 0; ks < 2; ++ks) {
;             if (ks == 1 && late && doi) { if (incur) issue(apc, bpc, cur.lda, cur.ldb, idx * 64, s0 ^ 1); else issue(apn, bpn, nxt.lda, nxt.ldb, 0, s0 ^ 1); }
;             bf16x8 af[8], bfr[4];
;             const int co = ((ks * 4 + fq) ^ sz) * 16;
; #pragma unroll
;             for (int m = 0; m < 8; ++m) af[m] = *(const bf16x8*)(As + (wr * 128 + m * 16 + fr) * 128 + co);
; #pragma unroll
;             for (int n = 0; n < 4; ++n) bfr[n] = *(const bf16x8*)(Bs + (wc * 64 + n * 16 + fr) * 128 + co);
; #pragma unroll
;             for (int m = 0; m < 8; ++m)
; #pragma unroll
;                 for (int n = 0; n < 4; ++n) acc[m][n] = __builtin_amdgcn_mfma_f32_16x16x32_bf16(bfr[n], af[m], acc[m][n], 0, 0, 0);
.Lp8_kloop:
	s_lshl_b32 s2, s75, 16
	s_xor_b32 s91, s2, 0x10000
	s_add_i32 s91, s71, s91
	v_add3_u32 v179, s2, v174, v178
	v_add3_u32 v160, s2, v174, v177
	v_add3_u32 v251, s2, v175, v178
	v_add3_u32 v250, s2, v175, v177
	ds_read_b128 v[180:183], v179 offset:32768
	ds_read_b128 v[184:187], v179 offset:34816
	ds_read_b128 v[188:191], v179 offset:36864
	ds_read_b128 v[192:195], v179 offset:38912
	ds_read_b128 v[230:233], v160
	ds_read_b128 v[234:237], v160 offset:2048
	ds_read_b128 v[238:241], v160 offset:4096
	ds_read_b128 v[242:245], v160 offset:6144
	v_lshl_add_u64 v[128:129], v[150:151], 0, s[86:87]
	v_lshl_add_u64 v[130:131], v[148:149], 0, s[86:87]
	v_mfma_f32_16x16x32_bf16 v[60:63], v[214:217], v[246:249], v[60:63]
	v_mfma_f32_16x16x32_bf16 v[56:59], v[218:221], v[246:249], v[56:59]
	v_mfma_f32_16x16x32_bf16 v[52:55], v[222:225], v[246:249], v[52:55]
	v_mfma_f32_16x16x32_bf16 v[48:51], v[226:229], v[246:249], v[48:51]
	s_mov_b64 s[80:81], 0x669b080
	v_lshl_add_u64 v[162:163], v[128:129], 0, s[80:81]
	s_mov_b32 m0, s91
	s_nop 0
	global_load_lds_dwordx4 v[162:163], off
	v_mfma_f32_16x16x32_bf16 v[44:47], v[214:217], v[196:199], v[44:47]
	v_mfma_f32_16x16x32_bf16 v[40:43], v[218:221], v[196:199], v[40:43]
	v_mfma_f32_16x16x32_bf16 v[36:39], v[222:225], v[196:199], v[36:39]
	v_mfma_f32_16x16x32_bf16 v[32:35], v[226:229], v[196:199], v[32:35]
	s_mov_b64 s[80:81], 0x66f3080
	v_lshl_add_u64 v[164:165], v[128:129], 0, s[80:81]
	s_add_i32 m0, s91, 0x2000
	s_nop 0
	global_load_lds_dwordx4 v[164:165], off
	v_mfma_f32_16x16x32_bf16 v[28:31], v[214:217], v[152:155], v[28:31]
	v_mfma_f32_16x16x32_bf16 v[24:27], v[218:221], v[152:155], v[24:27]
	v_mfma_f32_16x16x32_bf16 v[20:23], v[222:225], v[152:155], v[20:23]
	v_mfma_f32_16x16x32_bf16 v[16:19], v[226:229], v[152:155], v[16:19]
	s_mov_b64 s[80:81], 0x674b080
	v_lshl_add_u64 v[162:163], v[128:129], 0, s[80:81]
	s_add_i32 m0, s91, 0x4000
	s_nop 0
	global_load_lds_dwordx4 v[162:163], off
	v_mfma_f32_16x16x32_bf16 v[12:15], v[214:217], v[156:159], v[12:15]
	v_mfma_f32_16x16x32_bf16 v[4:7], v[218:221], v[156:159], v[4:7]
	v_mfma_f32_16x16x32_bf16 v[0:3], v[222:225], v[156:159], v[0:3]
	v_mfma_f32_16x16x32_bf16 v[8:11], v[226:229], v[156:159], v[8:11]
	s_mov_b64 s[80:81], 0x67a3080
	v_lshl_add_u64 v[164:165], v[128:129], 0, s[80:81]
	s_add_i32 m0, s91, 0x6000
	s_nop 0
	global_load_lds_dwordx4 v[164:165], off
	s_waitcnt lgkmcnt(0)
	ds_read_b128 v[214:217], v251 offset:32768
	ds_read_b128 v[218:221], v251 offset:34816
	ds_read_b128 v[222:225], v251 offset:36864
	ds_read_b128 v[226:229], v251 offset:38912
	ds_read_b128 v[246:249], v160 offset:8192
	ds_read_b128 v[196:199], v160 offset:10240
	ds_read_b128 v[152:155], v160 offset:12288
	ds_read_b128 v[156:159], v160 offset:14336
	v_mfma_f32_16x16x32_bf16 v[124:127], v[180:183], v[230:233], v[124:127]
	v_mfma_f32_16x16x32_bf16 v[120:123], v[184:187], v[230:233], v[120:123]
	v_mfma_f32_16x16x32_bf16 v[116:119], v[188:191], v[230:233], v[116:119]
	v_mfma_f32_16x16x32_bf16 v[112:115], v[192:195], v[230:233], v[112:115]
	s_mov_b64 s[80:81], 0x1f52080
	v_lshl_add_u64 v[162:163], v[130:131], 0, s[80:81]
	s_add_i32 m0, s91, 0x8000
	s_nop 0
	global_load_lds_dwordx4 v[162:163], off
	ds_read_b128 v[230:233], v250
	v_mfma_f32_16x16x32_bf16 v[108:111], v[180:183], v[234:237], v[108:111]
	v_mfma_f32_16x16x32_bf16 v[104:107], v[184:187], v[234:237], v[104:107]
	v_mfma_f32_16x16x32_bf16 v[100:103], v[188:191], v[234:237], v[100:103]
	v_mfma_f32_16x16x32_bf16 v[96:99], v[192:195], v[234:237], v[96:99]
	s_mov_b64 s[80:81], 0x1faa080
	v_lshl_add_u64 v[164:165], v[130:131], 0, s[80:81]
	s_add_i32 m0, s91, 0xa000
	s_nop 0
	global_load_lds_dwordx4 v[164:165], off
	ds_read_b128 v[234:237], v250 offset:2048
	v_mfma_f32_16x16x32_bf16 v[92:95], v[180:183], v[238:241], v[92:95]
	v_mfma_f32_16x16x32_bf16 v[88:91], v[184:187], v[238:241], v[88:91]
	v_mfma_f32_16x16x32_bf16 v[84:87], v[188:191], v[238:241], v[84:87]
	v_mfma_f32_16x16x32_bf16 v[80:83], v[192:195], v[238:241], v[80:83]
	s_mov_b64 s[80:81], 0x2002080
	v_lshl_add_u64 v[162:163], v[130:131], 0, s[80:81]
	s_add_i32 m0, s91, 0xc000
	s_nop 0
	global_load_lds_dwordx4 v[162:163], off
	ds_read_b128 v[238:241], v250 offset:4096
	v_mfma_f32_16x16x32_bf16 v[76:79], v[180:183], v[242:245], v[76:79]
	v_mfma_f32_16x16x32_bf16 v[72:75], v[184:187], v[242:245], v[72:75]
	v_mfma_f32_16x16x32_bf16 v[68:71], v[188:191], v[242:245], v[68:71]
	v_mfma_f32_16x16x32_bf16 v[64:67], v[192:195], v[242:245], v[64:67]
	s_mov_b64 s[80:81], 0x205a080
	v_lshl_add_u64 v[164:165], v[130:131], 0, s[80:81]
	s_add_i32 m0, s91, 0xe000
	s_nop 0
	global_load_lds_dwordx4 v[164:165], off
	ds_read_b128 v[242:245], v250 offset:6144
	s_waitcnt lgkmcnt(7)
	v_mfma_f32_16x16x32_bf16 v[60:63], v[180:183], v[246:249], v[60:63]
	v_mfma_f32_16x16x32_bf16 v[56:59], v[184:187], v[246:249], v[56:59]
	v_mfma_f32_16x16x32_bf16 v[52:55], v[188:191], v[246:249], v[52:55]
	v_mfma_f32_16x16x32_bf16 v[48:51], v[192:195], v[246:249], v[48:51]
	ds_read_b128 v[246:249], v250 offset:8192
	s_waitcnt lgkmcnt(7)
	v_mfma_f32_16x16x32_bf16 v[44:47], v[180:183], v[196:199], v[44:47]
	v_mfma_f32_16x16x32_bf16 v[40:43], v[184:187], v[196:199], v[40:43]
	v_mfma_f32_16x16x32_bf16 v[36:39], v[188:191], v[196:199], v[36:39]
	v_mfma_f32_16x16x32_bf16 v[32:35], v[192:195], v[196:199], v[32:35]
	ds_read_b128 v[196:199], v250 offset:10240
	s_waitcnt lgkmcnt(7)
	v_mfma_f32_16x16x32_bf16 v[28:31], v[180:183], v[152:155], v[28:31]
	v_mfma_f32_16x16x32_bf16 v[24:27], v[184:187], v[152:155], v[24:27]
	v_mfma_f32_16x16x32_bf16 v[20:23], v[188:191], v[152:155], v[20:23]
	v_mfma_f32_16x16x32_bf16 v[16:19], v[192:195], v[152:155], v[16:19]
	ds_read_b128 v[152:155], v250 offset:12288
	s_waitcnt lgkmcnt(7)
; __device__ __forceinline__ void gemm_stream256(f32x4 (&acc)[8][4], const Seg& cur, const Seg& nxt, bool has_next, bool first, int& st, unsigned char* lds, int tid) {
;     ...
;     for (int kt = 0; kt < nk; ++kt) {
;         const int idx = kt + 1;
;         const bool incur = idx < nk, doi = incur || has_next;
;         if (!late && doi) { if (incur) issue(apc, bpc, cur.lda, cur.ldb, idx * 64, s0 ^ 1); else issue(apn, bpn, nxt.lda, nxt.ldb, 0, s0 ^ 1); }
;         const unsigned char* As = lds + s0 * STAGE;
;         const unsigned char* Bs = As + 256 * 128;
; #pragma unroll
;         for (int ks = 0; ks < 2; ++ks) {
;             if (ks == 1 && late && doi) { if (incur) issue(apc, bpc, cur.lda, cur.ldb, idx * 64, s0 ^ 1); else issue(apn, bpn, nxt.lda, nxt.ldb, 0, s0 ^ 1); }
;             bf16x8 af[8], bfr[4];
;             const int co = ((ks * 4 + fq) ^ sz) * 16;
; #pragma unroll
;             for (int m = 0; m < 8; ++m) af[m] = *(const bf16x8*)(As + (wr * 128 + m * 16 + fr) * 128 + co);
; #pragma unroll
;             for (int n = 0; n < 4; ++n) bfr[n] = *(const bf16x8*)(Bs + (wc * 64 + n * 16 + fr) * 128 + co);
; #pragma unroll
;             for (int m = 0; m < 8; ++m)
; #pragma unroll
;                 for (int n = 0; n < 4; ++n) acc[m][n] = __builtin_amdgcn_mfma_f32_16x16x32_bf16(bfr[n], af[m], acc[m][n], 0, 0, 0);
;         }
;         asm volatile("s_waitcnt vmcnt(0) lgkmcnt(0)" ::: "memory");
;         __builtin_amdgcn_s_barrier();
;         asm volatile("" ::: "memory");
;         s0 ^= 1;
;     }
	v_mfma_f32_16x16x32_bf16 v[12:15], v[180:183], v[156:159], v[12:15]
	v_mfma_f32_16x16x32_bf16 v[4:7], v[184:187], v[156:159], v[4:7]
	v_mfma_f32_16x16x32_bf16 v[0:3], v[188:191], v[156:159], v[0:3]
	v_mfma_f32_16x16x32_bf16 v[8:11], v[192:195], v[156:159], v[8:11]
	ds_read_b128 v[156:159], v250 offset:14336
	s_waitcnt lgkmcnt(7)
	v_mfma_f32_16x16x32_bf16 v[124:127], v[214:217], v[230:233], v[124:127]
	v_mfma_f32_16x16x32_bf16 v[120:123], v[218:221], v[230:233], v[120:123]
	v_mfma_f32_16x16x32_bf16 v[116:119], v[222:225], v[230:233], v[116:119]
	v_mfma_f32_16x16x32_bf16 v[112:115], v[226:229], v[230:233], v[112:115]
	s_waitcnt lgkmcnt(6)
	v_mfma_f32_16x16x32_bf16 v[108:111], v[214:217], v[234:237], v[108:111]
	v_mfma_f32_16x16x32_bf16 v[104:107], v[218:221], v[234:237], v[104:107]
	v_mfma_f32_16x16x32_bf16 v[100:103], v[222:225], v[234:237], v[100:103]
	v_mfma_f32_16x16x32_bf16 v[96:99], v[226:229], v[234:237], v[96:99]
	s_waitcnt lgkmcnt(5)
	v_mfma_f32_16x16x32_bf16 v[92:95], v[214:217], v[238:241], v[92:95]
	v_mfma_f32_16x16x32_bf16 v[88:91], v[218:221], v[238:241], v[88:91]
	v_mfma_f32_16x16x32_bf16 v[84:87], v[222:225], v[238:241], v[84:87]
	v_mfma_f32_16x16x32_bf16 v[80:83], v[226:229], v[238:241], v[80:83]
	s_waitcnt lgkmcnt(4)
	v_mfma_f32_16x16x32_bf16 v[76:79], v[214:217], v[242:245], v[76:79]
	v_mfma_f32_16x16x32_bf16 v[72:75], v[218:221], v[242:245], v[72:75]
	v_mfma_f32_16x16x32_bf16 v[68:71], v[222:225], v[242:245], v[68:71]
	v_mfma_f32_16x16x32_bf16 v[64:67], v[226:229], v[242:245], v[64:67]
	s_add_u32 s86, s86, 0x80
	s_cmpk_eq_i32 s86, 0x1580
	s_cselect_b32 s86, 0, s86
	s_add_i32 s90, s90, 1
	s_xor_b32 s75, s75, 1
	s_waitcnt vmcnt(0) lgkmcnt(0)
	s_barrier
	s_cmpk_lg_i32 s90, 43
	s_cbranch_scc1 .Lp8_kloop
	s_lshl_b32 s2, s75, 16
	s_xor_b32 s91, s2, 0x10000
	s_add_i32 s91, s71, s91
	v_add3_u32 v179, s2, v174, v178
	v_add3_u32 v160, s2, v174, v177
	v_add3_u32 v251, s2, v175, v178
	v_add3_u32 v250, s2, v175, v177
	ds_read_b128 v[180:183], v179 offset:32768
	ds_read_b128 v[184:187], v179 offset:34816
	ds_read_b128 v[188:191], v179 offset:36864
	ds_read_b128 v[192:195], v179 offset:38912
	ds_read_b128 v[230:233], v160
	ds_read_b128 v[234:237], v160 offset:2048
	ds_read_b128 v[238:241], v160 offset:4096
	ds_read_b128 v[242:245], v160 offset:6144
	v_mfma_f32_16x16x32_bf16 v[60:63], v[214:217], v[246:249], v[60:63]
	v_mfma_f32_16x16x32_bf16 v[56:59], v[218:221], v[246:249], v[56:59]
	v_mfma_f32_16x16x32_bf16 v[52:55], v[222:225], v[246:249], v[52:55]
	v_mfma_f32_16x16x32_bf16 v[48:51], v[226:229], v[246:249], v[48:51]
	v_mfma_f32_16x16x32_bf16 v[44:47], v[214:217], v[196:199], v[44:47]
	v_mfma_f32_16x16x32_bf16 v[40:43], v[218:221], v[196:199], v[40:43]
	v_mfma_f32_16x16x32_bf16 v[36:39], v[222:225], v[196:199], v[36:39]
	v_mfma_f32_16x16x32_bf16 v[32:35], v[226:229], v[196:199], v[32:35]
	v_mfma_f32_16x16x32_bf16 v[28:31], v[214:217], v[152:155], v[28:31]
	v_mfma_f32_16x16x32_bf16 v[24:27], v[218:221], v[152:155], v[24:27]
	v_mfma_f32_16x16x32_bf16 v[20:23], v[222:225], v[152:155], v[20:23]
	v_mfma_f32_16x16x32_bf16 v[16:19], v[226:229], v[152:155], v[16:19]
	v_mfma_f32_16x16x32_bf16 v[12:15], v[214:217], v[156:159], v[12:15]
	v_mfma_f32_16x16x32_bf16 v[4:7], v[218:221], v[156:159], v[4:7]
	v_mfma_f32_16x16x32_bf16 v[0:3], v[222:225], v[156:159], v[0:3]
	v_mfma_f32_16x16x32_bf16 v[8:11], v[226:229], v[156:159], v[8:11]
	s_waitcnt lgkmcnt(0)
	ds_read_b128 v[214:217], v251 offset:32768
	ds_read_b128 v[218:221], v251 offset:34816
	ds_read_b128 v[222:225], v251 offset:36864
	ds_read_b128 v[226:229], v251 offset:38912
	ds_read_b128 v[246:249], v160 offset:8192
	ds_read_b128 v[196:199], v160 offset:10240
	ds_read_b128 v[152:155], v160 offset:12288
	ds_read_b128 v[156:159], v160 offset:14336
	v_mfma_f32_16x16x32_bf16 v[124:127], v[180:183], v[230:233], v[124:127]
	v_mfma_f32_16x16x32_bf16 v[120:123], v[184:187], v[230:233], v[120:123]
	v_mfma_f32_16x16x32_bf16 v[116:119], v[188:191], v[230:233], v[116:119]
	v_mfma_f32_16x16x32_bf16 v[112:115], v[192:195], v[230:233], v[112:115]
	ds_read_b128 v[230:233], v250
	v_mfma_f32_16x16x32_bf16 v[108:111], v[180:183], v[234:237], v[108:111]
	v_mfma_f32_16x16x32_bf16 v[104:107], v[184:187], v[234:237], v[104:107]
	v_mfma_f32_16x16x32_bf16 v[100:103], v[188:191], v[234:237], v[100:103]
	v_mfma_f32_16x16x32_bf16 v[96:99], v[192:195], v[234:237], v[96:99]
	ds_read_b128 v[234:237], v250 offset:2048
	v_mfma_f32_16x16x32_bf16 v[92:95], v[180:183], v[238:241], v[92:95]
	v_mfma_f32_16x16x32_bf16 v[88:91], v[184:187], v[238:241], v[88:91]
	v_mfma_f32_16x16x32_bf16 v[84:87], v[188:191], v[238:241], v[84:87]
	v_mfma_f32_16x16x32_bf16 v[80:83], v[192:195], v[238:241], v[80:83]
	ds_read_b128 v[238:241], v250 offset:4096
	v_mfma_f32_16x16x32_bf16 v[76:79], v[180:183], v[242:245], v[76:79]
	v_mfma_f32_16x16x32_bf16 v[72:75], v[184:187], v[242:245], v[72:75]
	v_mfma_f32_16x16x32_bf16 v[68:71], v[188:191], v[242:245], v[68:71]
	v_mfma_f32_16x16x32_bf16 v[64:67], v[192:195], v[242:245], v[64:67]
	ds_read_b128 v[242:245], v250 offset:6144
	s_waitcnt lgkmcnt(7)
; __device__ __forceinline__ void gemm_stream256(f32x4 (&acc)[8][4], const Seg& cur, const Seg& nxt, bool has_next, bool first, int& st, unsigned char* lds, int tid) {
;     ...
;         for (int ks = 0; ks < 2; ++ks) {
;             if (ks == 1 && late && doi) { if (incur) issue(apc, bpc, cur.lda, cur.ldb, idx * 64, s0 ^ 1); else issue(apn, bpn, nxt.lda, nxt.ldb, 0, s0 ^ 1); }
;             bf16x8 af[8], bfr[4];
;             const int co = ((ks * 4 + fq) ^ sz) * 16;
; #pragma unroll
;             for (int m = 0; m < 8; ++m) af[m] = *(const bf16x8*)(As + (wr * 128 + m * 16 + fr) * 128 + co);
; #pragma unroll
;             for (int n = 0; n < 4; ++n) bfr[n] = *(const bf16x8*)(Bs + (wc * 64 + n * 16 + fr) * 128 + co);
; #pragma unroll
;             for (int m = 0; m < 8; ++m)
; #pragma unroll
;                 for (int n = 0; n < 4; ++n) acc[m][n] = __builtin_amdgcn_mfma_f32_16x16x32_bf16(bfr[n], af[m], acc[m][n], 0, 0, 0);
;         }
;         asm volatile("s_waitcnt vmcnt(0) lgkmcnt(0)" ::: "memory");
;         __builtin_amdgcn_s_barrier();
;         asm volatile("" ::: "memory");
;         s0 ^= 1;
;     }
	v_mfma_f32_16x16x32_bf16 v[60:63], v[180:183], v[246:249], v[60:63]
	v_mfma_f32_16x16x32_bf16 v[56:59], v[184:187], v[246:249], v[56:59]
	v_mfma_f32_16x16x32_bf16 v[52:55], v[188:191], v[246:249], v[52:55]
	v_mfma_f32_16x16x32_bf16 v[48:51], v[192:195], v[246:249], v[48:51]
	ds_read_b128 v[246:249], v250 offset:8192
	s_waitcnt lgkmcnt(7)
	v_mfma_f32_16x16x32_bf16 v[44:47], v[180:183], v[196:199], v[44:47]
	v_mfma_f32_16x16x32_bf16 v[40:43], v[184:187], v[196:199], v[40:43]
	v_mfma_f32_16x16x32_bf16 v[36:39], v[188:191], v[196:199], v[36:39]
	v_mfma_f32_16x16x32_bf16 v[32:35], v[192:195], v[196:199], v[32:35]
	ds_read_b128 v[196:199], v250 offset:10240
	s_waitcnt lgkmcnt(7)
	v_mfma_f32_16x16x32_bf16 v[28:31], v[180:183], v[152:155], v[28:31]
	v_mfma_f32_16x16x32_bf16 v[24:27], v[184:187], v[152:155], v[24:27]
	v_mfma_f32_16x16x32_bf16 v[20:23], v[188:191], v[152:155], v[20:23]
	v_mfma_f32_16x16x32_bf16 v[16:19], v[192:195], v[152:155], v[16:19]
	ds_read_b128 v[152:155], v250 offset:12288
	s_waitcnt lgkmcnt(7)
	v_mfma_f32_16x16x32_bf16 v[12:15], v[180:183], v[156:159], v[12:15]
	v_mfma_f32_16x16x32_bf16 v[4:7], v[184:187], v[156:159], v[4:7]
	v_mfma_f32_16x16x32_bf16 v[0:3], v[188:191], v[156:159], v[0:3]
	v_mfma_f32_16x16x32_bf16 v[8:11], v[192:195], v[156:159], v[8:11]
	ds_read_b128 v[156:159], v250 offset:14336
	s_waitcnt lgkmcnt(7)
	v_mfma_f32_16x16x32_bf16 v[124:127], v[214:217], v[230:233], v[124:127]
	v_mfma_f32_16x16x32_bf16 v[120:123], v[218:221], v[230:233], v[120:123]
	v_mfma_f32_16x16x32_bf16 v[116:119], v[222:225], v[230:233], v[116:119]
	v_mfma_f32_16x16x32_bf16 v[112:115], v[226:229], v[230:233], v[112:115]
	s_waitcnt lgkmcnt(6)
	v_mfma_f32_16x16x32_bf16 v[108:111], v[214:217], v[234:237], v[108:111]
	v_mfma_f32_16x16x32_bf16 v[104:107], v[218:221], v[234:237], v[104:107]
	v_mfma_f32_16x16x32_bf16 v[100:103], v[222:225], v[234:237], v[100:103]
	v_mfma_f32_16x16x32_bf16 v[96:99], v[226:229], v[234:237], v[96:99]
	s_waitcnt lgkmcnt(5)
	v_mfma_f32_16x16x32_bf16 v[92:95], v[214:217], v[238:241], v[92:95]
	v_mfma_f32_16x16x32_bf16 v[88:91], v[218:221], v[238:241], v[88:91]
	v_mfma_f32_16x16x32_bf16 v[84:87], v[222:225], v[238:241], v[84:87]
	v_mfma_f32_16x16x32_bf16 v[80:83], v[226:229], v[238:241], v[80:83]
	s_waitcnt lgkmcnt(4)
	v_mfma_f32_16x16x32_bf16 v[76:79], v[214:217], v[242:245], v[76:79]
	v_mfma_f32_16x16x32_bf16 v[72:75], v[218:221], v[242:245], v[72:75]
	v_mfma_f32_16x16x32_bf16 v[68:71], v[222:225], v[242:245], v[68:71]
	v_mfma_f32_16x16x32_bf16 v[64:67], v[226:229], v[242:245], v[64:67]
	s_waitcnt lgkmcnt(3)
	v_mfma_f32_16x16x32_bf16 v[60:63], v[214:217], v[246:249], v[60:63]
	v_mfma_f32_16x16x32_bf16 v[56:59], v[218:221], v[246:249], v[56:59]
	v_mfma_f32_16x16x32_bf16 v[52:55], v[222:225], v[246:249], v[52:55]
	v_mfma_f32_16x16x32_bf16 v[48:51], v[226:229], v[246:249], v[48:51]
	s_waitcnt lgkmcnt(2)
	v_mfma_f32_16x16x32_bf16 v[44:47], v[214:217], v[196:199], v[44:47]
	v_mfma_f32_16x16x32_bf16 v[40:43], v[218:221], v[196:199], v[40:43]
	v_mfma_f32_16x16x32_bf16 v[36:39], v[222:225], v[196:199], v[36:39]
	v_mfma_f32_16x16x32_bf16 v[32:35], v[226:229], v[196:199], v[32:35]
	s_waitcnt lgkmcnt(1)
	v_mfma_f32_16x16x32_bf16 v[28:31], v[214:217], v[152:155], v[28:31]
	v_mfma_f32_16x16x32_bf16 v[24:27], v[218:221], v[152:155], v[24:27]
	v_mfma_f32_16x16x32_bf16 v[20:23], v[222:225], v[152:155], v[20:23]
	v_mfma_f32_16x16x32_bf16 v[16:19], v[226:229], v[152:155], v[16:19]
	s_waitcnt lgkmcnt(0)
	v_mfma_f32_16x16x32_bf16 v[12:15], v[214:217], v[156:159], v[12:15]
	v_mfma_f32_16x16x32_bf16 v[4:7], v[218:221], v[156:159], v[4:7]
	v_mfma_f32_16x16x32_bf16 v[0:3], v[222:225], v[156:159], v[0:3]
	v_mfma_f32_16x16x32_bf16 v[8:11], v[226:229], v[156:159], v[8:11]
	s_waitcnt vmcnt(0) lgkmcnt(0)
	s_barrier
	s_setprio 0
	s_branch .LBB0_1074
